# attention step loop: 6-slot LDS ring (static LDS +24832 B), 4 tiles in flight, V-read wait moved off the barrier
# speedup vs baseline: 1.0343x; 1.0012x over previous
; #define RING_ISSUE(SI) do { int kbi = kb0 + (SI) * 32; if (kbi > kb_last) kbi = kb_last; const int slot = (SI) % 3; \
;           const h16* srcp = wave < 4 ? kbase + (size_t)kbi * LDH + k_src_off : vT + (size_t)(kbi >> 5) * 2048 + v_src_off; \
;           __builtin_amdgcn_global_load_lds((const unsigned*)srcp, (LAS unsigned*)(ring + slot * 8192 + stage_dst), 16, 0, 0); } while (0)
; DI void attn_phase(const Params& p, const int layer, const int wid_s) {
;     ...
;       const int kb_last = qblk * 64 + 32;
;       const int kmax_w = (t0 + 15) & ~31;
; #pragma unroll 1
;       for (int br = 1; br <= 2; ++br) {
;         const h16* kbase = hb + (br == 1 ? C_KS : C_KW) + g * 64;
;         const h16* vT = (const h16*)(p.ws + (br == 1 ? OFF_VST : OFF_VWT)) + (size_t)bg * 64 * SEQ;
;         int kb0 = 0, lo_w = 0;
;         if (br == 2) { kb0 = qblk * 64 - 512; if (kb0 < 0) kb0 = 0; lo_w = t0 - 511; if (lo_w < 0) lo_w = 0; lo_w &= ~31; }
;         const int nsteps = (kb_last - kb0) / 32 + 1;
;         f32x4 O[2][4]; float l[2];
; #pragma unroll
;         for (int hp = 0; hp < 2; ++hp) { l[hp] = 0.f;
; #pragma unroll
;           for (int dt = 0; dt < 4; ++dt) O[hp][dt] = (f32x4){0.f, 0.f, 0.f, 0.f}; }
;     ...
;         asm volatile("s_waitcnt vmcnt(0)" ::: "memory");
;         __syncthreads();
;         RING_ISSUE(0); RING_ISSUE(1);
.LBB0_345:
	s_add_i32 m0, s13, 0x1b880
	s_sub_i32 s13, s14, s12
	global_load_lds_dwordx4 v[2:3], off
	s_xor_b64 s[6:7], s[4:5], -1
	s_ashr_i32 s13, s13, 5
	v_mov_b32_e32 v3, 0
	s_cmp_lt_i32 s13, 0
	v_mov_b32_e32 v2, v3
	v_mov_b32_e32 v67, v3
	v_mov_b32_e32 v66, v3
	v_mov_b32_e32 v65, v3
	v_mov_b32_e32 v64, v3
	v_mov_b32_e32 v59, v3
	v_mov_b32_e32 v58, v3
	v_mov_b32_e32 v57, v3
	v_mov_b32_e32 v56, v3
	v_mov_b32_e32 v55, v3
	v_mov_b32_e32 v54, v3
	v_mov_b32_e32 v53, v3
	v_mov_b32_e32 v52, v3
	v_mov_b32_e32 v51, v3
	v_mov_b32_e32 v50, v3
	v_mov_b32_e32 v49, v3
	v_mov_b32_e32 v48, v3
	v_mov_b32_e32 v47, v3
	v_mov_b32_e32 v46, v3
	v_mov_b32_e32 v45, v3
	v_mov_b32_e32 v44, v3
	v_mov_b32_e32 v43, v3
	v_mov_b32_e32 v42, v3
	v_mov_b32_e32 v41, v3
	v_mov_b32_e32 v40, v3
	v_mov_b32_e32 v39, v3
	v_mov_b32_e32 v38, v3
	v_mov_b32_e32 v37, v3
	v_mov_b32_e32 v36, v3
	v_mov_b32_e32 v35, v3
	v_mov_b32_e32 v34, v3
	v_mov_b32_e32 v33, v3
	v_mov_b32_e32 v32, v3
	s_cbranch_scc1 .LBB0_368
	v_mov_b32_e32 v2, v1
	v_mov_b32_e32 v3, v1
	s_and_b64 s[40:41], s[4:5], exec
	v_lshl_add_u64 v[6:7], s[10:11], 0, v[0:1]
	v_mov_b32_e32 v0, v1
	v_mov_b32_e32 v32, 0
	v_mov_b64_e32 v[62:63], v[2:3]
	s_mov_b32 s39, 0
	s_cselect_b32 s40, s21, 0
	v_lshl_add_u64 v[152:153], v[144:145], 1, s[8:9]
	s_add_i32 s41, s13, 1
	s_add_i32 s42, s12, 0x1f1
	v_subrev_u32_e32 v151, s12, v195
	s_mov_b32 s43, 2
	s_mov_b32 s44, 0
	v_mov_b64_e32 v[60:61], v[0:1]
	v_mov_b32_e32 v33, v32
	v_mov_b32_e32 v34, v32
	v_mov_b32_e32 v35, v32
	v_mov_b32_e32 v48, v32
	v_mov_b32_e32 v49, v32
	v_mov_b32_e32 v50, v32
	v_mov_b32_e32 v51, v32
	v_mov_b32_e32 v36, v32
	v_mov_b32_e32 v37, v32
	v_mov_b32_e32 v38, v32
	v_mov_b32_e32 v39, v32
	v_mov_b32_e32 v52, v32
	v_mov_b32_e32 v53, v32
	v_mov_b32_e32 v54, v32
	v_mov_b32_e32 v55, v32
	v_mov_b32_e32 v40, v32
	v_mov_b32_e32 v41, v32
	v_mov_b32_e32 v42, v32
	v_mov_b32_e32 v43, v32
	v_mov_b32_e32 v56, v32
	v_mov_b32_e32 v57, v32
	v_mov_b32_e32 v58, v32
	v_mov_b32_e32 v59, v32
	v_mov_b32_e32 v44, v32
	v_mov_b32_e32 v45, v32
	v_mov_b32_e32 v46, v32
	v_mov_b32_e32 v47, v32
	v_mov_b32_e32 v2, v32
	v_mov_b32_e32 v3, v32
	v_mov_b32_e32 v64, v32
	v_mov_b32_e32 v65, v32
	v_mov_b32_e32 v66, v32
	v_mov_b32_e32 v67, v32
	s_movk_i32 s42, 0x1400
	s_and_b64 vcc, exec, s[30:31]
	s_cselect_b32 s42, 0x80, s42
	v_cndmask_b32_e32 v240, v152, v6, vcc
	v_cndmask_b32_e32 v241, v153, v7, vcc
	s_mov_b32 s45, s12
	s_mov_b32 s39, 0x19880
	s_mov_b32 s43, 0x1d880
	s_mov_b32 s44, 0
	s_mov_b32 s13, -1
	v_mov_b32_e32 v214, 0
	v_mov_b32_e32 v215, 0
	v_mov_b32_e32 v216, 0
	v_mov_b32_e32 v217, 0
	v_mov_b32_e32 v218, 0
	v_mov_b32_e32 v219, 0
	v_mov_b32_e32 v220, 0
	v_mov_b32_e32 v221, 0
	s_add_i32 s8, s45, 64
	s_min_i32 s8, s8, s14
	s_mul_i32 s8, s8, s42
	s_mov_b32 s9, 0
	v_lshl_add_u64 v[238:239], v[240:241], 0, s[8:9]
	s_add_i32 m0, s43, s22
	s_nop 0
	global_load_lds_dwordx4 v[238:239], off
	s_add_i32 s43, s43, 0x2000
	s_cmp_eq_u32 s43, 0x1f880
	s_cselect_b32 s43, 0x20080, s43
	s_cmp_eq_u32 s43, 0x26080
	s_cselect_b32 s43, 0x19880, s43
	s_add_i32 s8, s45, 96
	s_min_i32 s8, s8, s14
	s_mul_i32 s8, s8, s42
	s_mov_b32 s9, 0
	v_lshl_add_u64 v[238:239], v[240:241], 0, s[8:9]
	s_add_i32 m0, s43, s22
	s_nop 0
	global_load_lds_dwordx4 v[238:239], off
	s_add_i32 s43, s43, 0x2000
	s_cmp_eq_u32 s43, 0x1f880
	s_cselect_b32 s43, 0x20080, s43
	s_cmp_eq_u32 s43, 0x26080
	s_cselect_b32 s43, 0x19880, s43
	s_and_b64 vcc, exec, s[4:5]
	s_cbranch_vccnz .Lat_prewin
	v_mov_b32_e32 v242, v193
	v_mov_b32_e32 v243, v194
	v_mov_b32_e32 v244, v5
	v_bfrev_b32_e32 v247, 1
	s_branch .LBB0_349

; #define LAS __attribute__((address_space(3)))
; #define RING_ISSUE(SI) do { int kbi = kb0 + (SI) * 32; if (kbi > kb_last) kbi = kb_last; const int slot = (SI) % 3; \
;           const h16* srcp = wave < 4 ? kbase + (size_t)kbi * LDH + k_src_off : vT + (size_t)(kbi >> 5) * 2048 + v_src_off; \
;           __builtin_amdgcn_global_load_lds((const unsigned*)srcp, (LAS unsigned*)(ring + slot * 8192 + stage_dst), 16, 0, 0); } while (0)
; DI void attn_phase(const Params& p, const int layer, const int wid_s) {
;     ...
;         for (int si = 0; si < nsteps; ++si) {
;           asm volatile("s_waitcnt vmcnt(1) lgkmcnt(0)" ::: "memory");
;           __builtin_amdgcn_s_barrier();
;           asm volatile("" ::: "memory");
;           RING_ISSUE(si + 2);
;           const int kb = kb0 + si * 32;
;           if (kb > kmax_w || kb < lo_w) continue;
;           if (br == 1 && kb + 31 + 128 <= t0 && __ballot((selmask >> (kb >> 6)) & 1u) == 0ull) continue;
;           LAS unsigned char* slotp = ring + (si % 3) * 8192;
.LBB0_349:
	s_waitcnt vmcnt(3)
	s_barrier
	s_cmp_gt_i32 s45, s15
	s_cbranch_scc1 .Lat_skip
	s_cmp_lt_i32 s45, s40
	s_cbranch_scc1 .Lat_skip
	s_add_i32 s10, s45, 0x9f
	s_cmp_gt_i32 s10, s51
	s_cselect_b32 s11, 2, 0
	s_add_i32 s10, s45, 0x1f1
	s_cmp_le_i32 s10, s51
	s_cselect_b32 s10, 2, 0
	s_and_b32 s10, s10, s4
	s_or_b32 s11, s11, s10
	s_cmp_lg_u32 s11, 0
	s_cbranch_scc1 .Lat_comp
	s_and_b64 vcc, exec, s[4:5]
	s_cbranch_vccnz .Lat_comp
	s_lshr_b32 s10, s45, 6
	v_bfe_u32 v0, v5, s10, 1
	v_cmp_ne_u32_e32 vcc, 0, v0
	s_cmp_lg_u64 vcc, 0
	s_cbranch_scc0 .Lat_skip
.Lat_comp:
	v_add_u32_e32 v0, s39, v185
	v_add_u32_e32 v64, s39, v184
	ds_read_b128 v[96:99], v0
	ds_read_b128 v[92:95], v64
	ds_read_b128 v[88:91], v0 offset:2048
	ds_read_b128 v[84:87], v64 offset:2048
	s_add_i32 s8, s45, 128
	s_min_i32 s8, s8, s14
	s_mul_i32 s8, s8, s42
	s_mov_b32 s9, 0
	v_lshl_add_u64 v[238:239], v[240:241], 0, s[8:9]
	s_add_i32 m0, s43, s22
	s_nop 0
	global_load_lds_dwordx4 v[238:239], off
	s_add_i32 s43, s43, 0x2000
	s_cmp_eq_u32 s43, 0x1f880
	s_cselect_b32 s43, 0x20080, s43
	s_cmp_eq_u32 s43, 0x26080
	s_cselect_b32 s43, 0x19880, s43
	s_lshr_b32 s10, s45, 6
	s_cmp_eq_u32 s10, s13
	s_cbranch_scc1 .Lat_cok_c
	s_mov_b32 s13, s10
	v_bfe_u32 v65, v244, s10, 1
	v_cmp_ne_u32_e32 vcc, 0, v65
	s_nop 1
	v_cndmask_b32_e32 v128, v4, v242, vcc
	v_cndmask_b32_e32 v132, v4, v243, vcc
	v_cndmask_b32_e32 v129, v4, v242, vcc
	v_cndmask_b32_e32 v133, v4, v243, vcc
	v_cndmask_b32_e32 v130, v4, v242, vcc
	v_cndmask_b32_e32 v134, v4, v243, vcc
	v_cndmask_b32_e32 v131, v4, v242, vcc
	v_cndmask_b32_e32 v135, v4, v243, vcc

; #define MFMA16(a, b, c) __builtin_amdgcn_mfma_f32_16x16x32_f16((a), (b), (c), 0, 0, 0)
; #define RING_ISSUE(SI) do { int kbi = kb0 + (SI) * 32; if (kbi > kb_last) kbi = kb_last; const int slot = (SI) % 3; \
;           const h16* srcp = wave < 4 ? kbase + (size_t)kbi * LDH + k_src_off : vT + (size_t)(kbi >> 5) * 2048 + v_src_off; \
;           __builtin_amdgcn_global_load_lds((const unsigned*)srcp, (LAS unsigned*)(ring + slot * 8192 + stage_dst), 16, 0, 0); } while (0)
; template <bool SEL, bool GEN>
; DI void attn_step(const KF& kv, const int kb, const int t, const int lane, const bool selbit,
;                   const LAS float* tabh, const half8 (&q)[2][2], f32x4 (&O)[2][4], const float (&nR)[2], float (&l)[2]) {
;     ...
;   if (GEN) {
;     const int d0 = t - kb - fq * 4;
; #pragma unroll
;     for (int kt = 0; kt < 2; ++kt)
; #pragma unroll
;       for (int j = 0; j < 4; ++j) {
;         const int dist = d0 - (kt * 16 + j);
;         const bool bad = SEL ? (dist < 0) : ((unsigned)dist >= 512u);
;         const int ix = bad ? 130 : (dist > 128 ? 128 : dist);
; #pragma unroll
;         for (int hp = 0; hp < 2; ++hp) s[hp][kt][j] += tabh[hp * 132 + ix];
;       }
;   }
;   half8 pf[2];
; #pragma unroll
;   for (int hp = 0; hp < 2; ++hp) {
;     f32x4 p0, p1;
; #pragma unroll
;     for (int j = 0; j < 4; ++j) { p0[j] = __builtin_amdgcn_exp2f(s[hp][0][j]); p1[j] = __builtin_amdgcn_exp2f(s[hp][1][j]); }
;     l[hp] += ((p0[0] + p0[1]) + (p0[2] + p0[3])) + ((p1[0] + p1[1]) + (p1[2] + p1[3]));
;     pf[hp] = pack8(p0, p1);
;   }
; #pragma unroll
;   for (int dt = 0; dt < 4; ++dt)
; #pragma unroll
;     for (int hp = 0; hp < 2; ++hp) O[hp][dt] = MFMA16(kv.v[dt], pf[hp], O[hp][dt]);
; DI void attn_phase(const Params& p, const int layer, const int wid_s) {
;     ...
;           RING_ISSUE(si + 2);
;           const int kb = kb0 + si * 32;
;           if (kb > kmax_w || kb < lo_w) continue;
.Lat_skip:
	s_add_i32 s8, s45, 128
	s_min_i32 s8, s8, s14
	s_mul_i32 s8, s8, s42
	s_mov_b32 s9, 0
	v_lshl_add_u64 v[238:239], v[240:241], 0, s[8:9]
	s_add_i32 m0, s43, s22
	s_nop 0
	global_load_lds_dwordx4 v[238:239], off
	s_add_i32 s43, s43, 0x2000
	s_cmp_eq_u32 s43, 0x1f880
	s_cselect_b32 s43, 0x20080, s43
	s_cmp_eq_u32 s43, 0x26080
	s_cselect_b32 s43, 0x19880, s43
	s_bitcmp1_b32 s44, 0
	s_cbranch_scc0 .Lat_next
	s_bitcmp1_b32 s44, 1
	s_cbranch_scc0 .Lat_nogen_s
	v_add_u32_e32 v116, 19, v246
	v_add_u32_e32 v117, 18, v246
	v_cmp_gt_u32_e64 s[8:9], v247, v116
	v_cmp_gt_u32_e64 vcc, v247, v117
	v_min_u32_e32 v116, 0x80, v116
	v_min_u32_e32 v117, 0x80, v117
	v_cndmask_b32_e64 v116, v161, v116, s[8:9]
	v_cndmask_b32_e64 v117, v161, v117, vcc
	v_lshl_add_u32 v116, v116, 2, s38
	v_lshl_add_u32 v117, v117, 2, s38
	ds_read2_b32 v[222:223], v116 offset1:132
	ds_read2_b32 v[224:225], v117 offset1:132
	v_add_u32_e32 v116, 17, v246
	v_add_u32_e32 v117, 16, v246
	v_cmp_gt_u32_e64 s[8:9], v247, v116
	v_cmp_gt_u32_e64 vcc, v247, v117
	v_min_u32_e32 v116, 0x80, v116
	v_min_u32_e32 v117, 0x80, v117
	v_cndmask_b32_e64 v116, v161, v116, s[8:9]
	v_cndmask_b32_e64 v117, v161, v117, vcc
	v_lshl_add_u32 v116, v116, 2, s38
	v_lshl_add_u32 v117, v117, 2, s38
	ds_read2_b32 v[226:227], v116 offset1:132
	ds_read2_b32 v[228:229], v117 offset1:132
	v_add_u32_e32 v116, 3, v246
	v_add_u32_e32 v117, 2, v246
	v_cmp_gt_u32_e64 s[8:9], v247, v116
	v_cmp_gt_u32_e64 vcc, v247, v117
	v_min_u32_e32 v116, 0x80, v116
	v_min_u32_e32 v117, 0x80, v117
	v_cndmask_b32_e64 v116, v161, v116, s[8:9]
	v_cndmask_b32_e64 v117, v161, v117, vcc
	v_lshl_add_u32 v116, v116, 2, s38
	v_lshl_add_u32 v117, v117, 2, s38
	ds_read2_b32 v[230:231], v116 offset1:132
	ds_read2_b32 v[232:233], v117 offset1:132
	v_add_u32_e32 v116, 1, v246
	v_add_u32_e32 v117, 0, v246
	v_cmp_gt_u32_e64 s[8:9], v247, v116
	v_cmp_gt_u32_e64 vcc, v247, v117
	v_min_u32_e32 v116, 0x80, v116
	v_min_u32_e32 v117, 0x80, v117
	v_cndmask_b32_e64 v116, v161, v116, s[8:9]
	v_cndmask_b32_e64 v117, v161, v117, vcc
	v_lshl_add_u32 v116, v116, 2, s38
	v_lshl_add_u32 v117, v117, 2, s38
	ds_read2_b32 v[234:235], v116 offset1:132
	ds_read2_b32 v[236:237], v117 offset1:132
	s_waitcnt lgkmcnt(0)
	v_add_f32_e32 v100, v100, v222
	v_add_f32_e32 v108, v108, v223
	v_add_f32_e32 v101, v101, v224
	v_add_f32_e32 v109, v109, v225
	v_add_f32_e32 v102, v102, v226
	v_add_f32_e32 v110, v110, v227
	v_add_f32_e32 v103, v103, v228
	v_add_f32_e32 v111, v111, v229
	v_add_f32_e32 v104, v104, v230
	v_add_f32_e32 v112, v112, v231
	v_add_f32_e32 v105, v105, v232
	v_add_f32_e32 v113, v113, v233
	v_add_f32_e32 v106, v106, v234
	v_add_f32_e32 v114, v114, v235
	v_add_f32_e32 v107, v107, v236
	v_add_f32_e32 v115, v115, v237
.Lat_nogen_s:
	v_exp_f32_e32 v198, v100
	v_exp_f32_e32 v199, v101
	v_exp_f32_e32 v200, v102
	v_exp_f32_e32 v201, v103
	v_exp_f32_e32 v202, v104
	v_exp_f32_e32 v203, v105
	v_exp_f32_e32 v204, v106
	v_exp_f32_e32 v205, v107
	v_exp_f32_e32 v206, v108
	v_exp_f32_e32 v207, v109
	v_exp_f32_e32 v208, v110
	v_exp_f32_e32 v209, v111
	v_exp_f32_e32 v210, v112
	v_exp_f32_e32 v211, v113
	v_exp_f32_e32 v212, v114
	v_exp_f32_e32 v213, v115
	v_cvt_pkrtz_f16_f32 v120, v198, v199
	v_cvt_pkrtz_f16_f32 v121, v200, v201
	v_cvt_pkrtz_f16_f32 v122, v202, v203
	v_cvt_pkrtz_f16_f32 v123, v204, v205
	v_cvt_pkrtz_f16_f32 v124, v206, v207
	v_cvt_pkrtz_f16_f32 v125, v208, v209
	v_cvt_pkrtz_f16_f32 v126, v210, v211
	v_cvt_pkrtz_f16_f32 v127, v212, v213
	s_waitcnt lgkmcnt(0)
	v_mfma_f32_16x16x32_f16 v[60:63], v[80:83], v[120:123], v[60:63]
	v_add_f32_e32 v214, v214, v198
	v_add_f32_e32 v215, v215, v199
	v_mfma_f32_16x16x32_f16 v[56:59], v[76:79], v[120:123], v[56:59]
	v_add_f32_e32 v216, v216, v200
	v_add_f32_e32 v217, v217, v201
	v_mfma_f32_16x16x32_f16 v[52:55], v[72:75], v[120:123], v[52:55]
	v_add_f32_e32 v214, v214, v202
	v_add_f32_e32 v215, v215, v203
	v_mfma_f32_16x16x32_f16 v[48:51], v[68:71], v[120:123], v[48:51]
	v_add_f32_e32 v216, v216, v204
	v_add_f32_e32 v217, v217, v205
	v_mfma_f32_16x16x32_f16 v[44:47], v[80:83], v[124:127], v[44:47]
	v_add_f32_e32 v218, v218, v206
	v_add_f32_e32 v219, v219, v207
	v_mfma_f32_16x16x32_f16 v[40:43], v[76:79], v[124:127], v[40:43]
	v_add_f32_e32 v220, v220, v208
	v_add_f32_e32 v221, v221, v209
	v_mfma_f32_16x16x32_f16 v[36:39], v[72:75], v[124:127], v[36:39]
	v_add_f32_e32 v218, v218, v210
	v_add_f32_e32 v219, v219, v211
	v_mfma_f32_16x16x32_f16 v[32:35], v[68:71], v[124:127], v[32:35]
	v_add_f32_e32 v220, v220, v212
	v_add_f32_e32 v221, v221, v213
	s_mov_b32 s44, 0
; #define MFMA16(a, b, c) __builtin_amdgcn_mfma_f32_16x16x32_f16((a), (b), (c), 0, 0, 0)
; #define RING_ISSUE(SI) do { int kbi = kb0 + (SI) * 32; if (kbi > kb_last) kbi = kb_last; const int slot = (SI) % 3; \
;           const h16* srcp = wave < 4 ? kbase + (size_t)kbi * LDH + k_src_off : vT + (size_t)(kbi >> 5) * 2048 + v_src_off; \
;           __builtin_amdgcn_global_load_lds((const unsigned*)srcp, (LAS unsigned*)(ring + slot * 8192 + stage_dst), 16, 0, 0); } while (0)
; template <bool SEL, bool GEN>
; DI void attn_step(const KF& kv, const int kb, const int t, const int lane, const bool selbit,
;                   const LAS float* tabh, const half8 (&q)[2][2], f32x4 (&O)[2][4], const float (&nR)[2], float (&l)[2]) {
;     ...
;   if (GEN) {
;     const int d0 = t - kb - fq * 4;
; #pragma unroll
;     for (int kt = 0; kt < 2; ++kt)
; #pragma unroll
;       for (int j = 0; j < 4; ++j) {
;         const int dist = d0 - (kt * 16 + j);
;         const bool bad = SEL ? (dist < 0) : ((unsigned)dist >= 512u);
;         const int ix = bad ? 130 : (dist > 128 ? 128 : dist);
; #pragma unroll
;         for (int hp = 0; hp < 2; ++hp) s[hp][kt][j] += tabh[hp * 132 + ix];
;       }
;   }
;   half8 pf[2];
; #pragma unroll
;   for (int hp = 0; hp < 2; ++hp) {
;     f32x4 p0, p1;
; #pragma unroll
;     for (int j = 0; j < 4; ++j) { p0[j] = __builtin_amdgcn_exp2f(s[hp][0][j]); p1[j] = __builtin_amdgcn_exp2f(s[hp][1][j]); }
;     l[hp] += ((p0[0] + p0[1]) + (p0[2] + p0[3])) + ((p1[0] + p1[1]) + (p1[2] + p1[3]));
;     pf[hp] = pack8(p0, p1);
;   }
; #pragma unroll
;   for (int dt = 0; dt < 4; ++dt)
; #pragma unroll
;     for (int hp = 0; hp < 2; ++hp) O[hp][dt] = MFMA16(kv.v[dt], pf[hp], O[hp][dt]);
; DI void attn_phase(const Params& p, const int layer, const int wid_s) {
;     ...
;         for (int si = 0; si < nsteps; ++si) {
;           asm volatile("s_waitcnt vmcnt(1) lgkmcnt(0)" ::: "memory");
;           __builtin_amdgcn_s_barrier();
;           asm volatile("" ::: "memory");
;           RING_ISSUE(si + 2);
.Lat_next:
	s_add_i32 s39, s39, 0x2000
	s_cmp_eq_u32 s39, 0x1f880
	s_cselect_b32 s39, 0x20080, s39
	s_cmp_eq_u32 s39, 0x26080
	s_cselect_b32 s39, 0x19880, s39
	s_add_i32 s45, s45, 32
	s_add_i32 s41, s41, -1
	s_cmp_lg_u32 s41, 0
	s_cbranch_scc1 .LBB0_349
	s_bitcmp1_b32 s44, 0
	s_cbranch_scc0 .Lat_done
	s_bitcmp1_b32 s44, 1
	s_cbranch_scc0 .Lat_nogen_x
	v_add_u32_e32 v116, 19, v246
	v_add_u32_e32 v117, 18, v246
	v_cmp_gt_u32_e64 s[8:9], v247, v116
	v_cmp_gt_u32_e64 vcc, v247, v117
	v_min_u32_e32 v116, 0x80, v116
	v_min_u32_e32 v117, 0x80, v117
	v_cndmask_b32_e64 v116, v161, v116, s[8:9]
	v_cndmask_b32_e64 v117, v161, v117, vcc
	v_lshl_add_u32 v116, v116, 2, s38
	v_lshl_add_u32 v117, v117, 2, s38
	ds_read2_b32 v[222:223], v116 offset1:132
	ds_read2_b32 v[224:225], v117 offset1:132
	v_add_u32_e32 v116, 17, v246
	v_add_u32_e32 v117, 16, v246
	v_cmp_gt_u32_e64 s[8:9], v247, v116
	v_cmp_gt_u32_e64 vcc, v247, v117
	v_min_u32_e32 v116, 0x80, v116
	v_min_u32_e32 v117, 0x80, v117
	v_cndmask_b32_e64 v116, v161, v116, s[8:9]
	v_cndmask_b32_e64 v117, v161, v117, vcc
	v_lshl_add_u32 v116, v116, 2, s38
	v_lshl_add_u32 v117, v117, 2, s38
	ds_read2_b32 v[226:227], v116 offset1:132
	ds_read2_b32 v[228:229], v117 offset1:132
	v_add_u32_e32 v116, 3, v246
	v_add_u32_e32 v117, 2, v246
	v_cmp_gt_u32_e64 s[8:9], v247, v116
	v_cmp_gt_u32_e64 vcc, v247, v117
	v_min_u32_e32 v116, 0x80, v116
	v_min_u32_e32 v117, 0x80, v117
	v_cndmask_b32_e64 v116, v161, v116, s[8:9]
	v_cndmask_b32_e64 v117, v161, v117, vcc
	v_lshl_add_u32 v116, v116, 2, s38
	v_lshl_add_u32 v117, v117, 2, s38
	ds_read2_b32 v[230:231], v116 offset1:132
	ds_read2_b32 v[232:233], v117 offset1:132
	v_add_u32_e32 v116, 1, v246
	v_add_u32_e32 v117, 0, v246
	v_cmp_gt_u32_e64 s[8:9], v247, v116
	v_cmp_gt_u32_e64 vcc, v247, v117
	v_min_u32_e32 v116, 0x80, v116
	v_min_u32_e32 v117, 0x80, v117
	v_cndmask_b32_e64 v116, v161, v116, s[8:9]
	v_cndmask_b32_e64 v117, v161, v117, vcc
	v_lshl_add_u32 v116, v116, 2, s38
	v_lshl_add_u32 v117, v117, 2, s38
	ds_read2_b32 v[234:235], v116 offset1:132
	ds_read2_b32 v[236:237], v117 offset1:132
	s_waitcnt lgkmcnt(0)
	v_add_f32_e32 v100, v100, v222
	v_add_f32_e32 v108, v108, v223
	v_add_f32_e32 v101, v101, v224
	v_add_f32_e32 v109, v109, v225
	v_add_f32_e32 v102, v102, v226
	v_add_f32_e32 v110, v110, v227
	v_add_f32_e32 v103, v103, v228
	v_add_f32_e32 v111, v111, v229
	v_add_f32_e32 v104, v104, v230
	v_add_f32_e32 v112, v112, v231
	v_add_f32_e32 v105, v105, v232
	v_add_f32_e32 v113, v113, v233
	v_add_f32_e32 v106, v106, v234
	v_add_f32_e32 v114, v114, v235
	v_add_f32_e32 v107, v107, v236
	v_add_f32_e32 v115, v115, v237
.Lat_nogen_x:
	v_exp_f32_e32 v198, v100
	v_exp_f32_e32 v199, v101
	v_exp_f32_e32 v200, v102
	v_exp_f32_e32 v201, v103
	v_exp_f32_e32 v202, v104
	v_exp_f32_e32 v203, v105
	v_exp_f32_e32 v204, v106
	v_exp_f32_e32 v205, v107
	v_exp_f32_e32 v206, v108
	v_exp_f32_e32 v207, v109
	v_exp_f32_e32 v208, v110
	v_exp_f32_e32 v209, v111
	v_exp_f32_e32 v210, v112
	v_exp_f32_e32 v211, v113
	v_exp_f32_e32 v212, v114
	v_exp_f32_e32 v213, v115
	v_cvt_pkrtz_f16_f32 v120, v198, v199
	v_cvt_pkrtz_f16_f32 v121, v200, v201
	v_cvt_pkrtz_f16_f32 v122, v202, v203
	v_cvt_pkrtz_f16_f32 v123, v204, v205
	v_cvt_pkrtz_f16_f32 v124, v206, v207
	v_cvt_pkrtz_f16_f32 v125, v208, v209
	v_cvt_pkrtz_f16_f32 v126, v210, v211
	v_cvt_pkrtz_f16_f32 v127, v212, v213
	s_waitcnt lgkmcnt(0)
	v_mfma_f32_16x16x32_f16 v[60:63], v[80:83], v[120:123], v[60:63]
	v_add_f32_e32 v214, v214, v198
	v_add_f32_e32 v215, v215, v199
	v_mfma_f32_16x16x32_f16 v[56:59], v[76:79], v[120:123], v[56:59]
	v_add_f32_e32 v216, v216, v200
	v_add_f32_e32 v217, v217, v201
	v_mfma_f32_16x16x32_f16 v[52:55], v[72:75], v[120:123], v[52:55]
	v_add_f32_e32 v214, v214, v202
	v_add_f32_e32 v215, v215, v203
	v_mfma_f32_16x16x32_f16 v[48:51], v[68:71], v[120:123], v[48:51]
	v_add_f32_e32 v216, v216, v204
	v_add_f32_e32 v217, v217, v205
	v_mfma_f32_16x16x32_f16 v[44:47], v[80:83], v[124:127], v[44:47]
	v_add_f32_e32 v218, v218, v206
	v_add_f32_e32 v219, v219, v207
	v_mfma_f32_16x16x32_f16 v[40:43], v[76:79], v[124:127], v[40:43]
	v_add_f32_e32 v220, v220, v208
	v_add_f32_e32 v221, v221, v209
	v_mfma_f32_16x16x32_f16 v[36:39], v[72:75], v[124:127], v[36:39]
	v_add_f32_e32 v218, v218, v210
	v_add_f32_e32 v219, v219, v211
	v_mfma_f32_16x16x32_f16 v[32:35], v[68:71], v[124:127], v[32:35]
	v_add_f32_e32 v220, v220, v212
	v_add_f32_e32 v221, v221, v213

; #define LAS __attribute__((address_space(3)))
; DI void attn_phase(const Params& p, const int layer, const int wid_s) {
;     ...
;       LAS unsigned char* ring = (LAS unsigned char*)smem + 104576;
;       int k_src_off, v_src_off;
;       { const int r = tid >> 3, cs = tid & 7, c = cs ^ (r & 7); k_src_off = r * LDH + c * 8; }
;       { const int i = tid & 255, r = i >> 2, cs = i & 3, c = cs ^ ((r >> 2) & 3); v_src_off = r * 32 + c * 8; }
;       const unsigned stage_dst = (unsigned)(wave < 4 ? wave * 1024 : 4096 + (wave - 4) * 1024);
	.amdhsa_kernel _Z9hymba_fwd6Params
		.amdhsa_group_segment_fixed_size 24832
		.amdhsa_private_segment_fixed_size 0
		.amdhsa_kernarg_size 424
		.amdhsa_user_sgpr_count 2
		.amdhsa_user_sgpr_dispatch_ptr 0
		.amdhsa_user_sgpr_queue_ptr 0
		.amdhsa_user_sgpr_kernarg_segment_ptr 1
		.amdhsa_user_sgpr_dispatch_id 0
		.amdhsa_user_sgpr_kernarg_preload_length 0
		.amdhsa_user_sgpr_kernarg_preload_offset 0
		.amdhsa_user_sgpr_private_segment_size 0
		.amdhsa_uses_dynamic_stack 0
		.amdhsa_enable_private_segment 0
		.amdhsa_system_sgpr_workgroup_id_x 1
		.amdhsa_system_sgpr_workgroup_id_y 0
		.amdhsa_system_sgpr_workgroup_id_z 0
		.amdhsa_system_sgpr_workgroup_info 0
		.amdhsa_system_vgpr_workitem_id 2
		.amdhsa_next_free_vgpr 253
		.amdhsa_next_free_sgpr 100
		.amdhsa_accum_offset 256
		.amdhsa_reserve_vcc 1
		.amdhsa_float_round_mode_32 0
		.amdhsa_float_round_mode_16_64 0
		.amdhsa_float_denorm_mode_32 3
		.amdhsa_float_denorm_mode_16_64 3
		.amdhsa_dx10_clamp 1
		.amdhsa_ieee_mode 1
		.amdhsa_fp16_overflow 0
		.amdhsa_tg_split 0
		.amdhsa_exception_fp_ieee_invalid_op 0
		.amdhsa_exception_fp_denorm_src 0
		.amdhsa_exception_fp_ieee_div_zero 0
		.amdhsa_exception_fp_ieee_overflow 0
		.amdhsa_exception_fp_ieee_underflow 0
		.amdhsa_exception_fp_ieee_inexact 0
		.amdhsa_exception_int_div_zero 0
	.end_amdhsa_kernel

; #define LAS __attribute__((address_space(3)))
; DI void attn_phase(const Params& p, const int layer, const int wid_s) {
;     ...
;       LAS unsigned char* ring = (LAS unsigned char*)smem + 104576;
;       int k_src_off, v_src_off;
;       { const int r = tid >> 3, cs = tid & 7, c = cs ^ (r & 7); k_src_off = r * LDH + c * 8; }
;       { const int i = tid & 255, r = i >> 2, cs = i & 3, c = cs ^ ((r >> 2) & 3); v_src_off = r * 32 + c * 8; }
;       const unsigned stage_dst = (unsigned)(wave < 4 ? wave * 1024 : 4096 + (wave - 4) * 1024);
amdhsa.kernels:
  - .agpr_count:     0
    .args:
      - .offset:         0
        .size:           168
        .value_kind:     by_value
      - .offset:         168
        .size:           4
        .value_kind:     hidden_block_count_x
      - .offset:         172
        .size:           4
        .value_kind:     hidden_block_count_y
      - .offset:         176
        .size:           4
        .value_kind:     hidden_block_count_z
      - .offset:         180
        .size:           2
        .value_kind:     hidden_group_size_x
      - .offset:         182
        .size:           2
        .value_kind:     hidden_group_size_y
      - .offset:         184
        .size:           2
        .value_kind:     hidden_group_size_z
      - .offset:         186
        .size:           2
        .value_kind:     hidden_remainder_x
      - .offset:         188
        .size:           2
        .value_kind:     hidden_remainder_y
      - .offset:         190
        .size:           2
        .value_kind:     hidden_remainder_z
      - .offset:         208
        .size:           8
        .value_kind:     hidden_global_offset_x
      - .offset:         216
        .size:           8
        .value_kind:     hidden_global_offset_y
      - .offset:         224
        .size:           8
        .value_kind:     hidden_global_offset_z
      - .offset:         232
        .size:           2
        .value_kind:     hidden_grid_dims
      - .offset:         256
        .size:           8
        .value_kind:     hidden_multigrid_sync_arg
      - .offset:         288
        .size:           4
        .value_kind:     hidden_dynamic_lds_size
    .group_segment_fixed_size: 24832
    .kernarg_segment_align: 8
    .kernarg_segment_size: 424
    .language:       OpenCL C
    .language_version:
      - 2
      - 0
    .max_flat_workgroup_size: 512
    .name:           _Z9hymba_fwd6Params
    .private_segment_fixed_size: 0
    .sgpr_count:     106
    .sgpr_spill_count: 267
    .symbol:         _Z9hymba_fwd6Params.kd
    .uniform_work_group_size: 1
    .uses_dynamic_stack: false
    .vgpr_count:     253
    .vgpr_spill_count: 0
    .wavefront_size: 64
